# in-proj slack late start plus up-proj start staggered in 4 groups 0.9 us apart
# baseline (speedup 1.0000x reference)
; #define PG8_STAGE(bufoff, gbase, voff) do { _Pragma("unroll") for (int _i = 0; _i < 2; ++_i) \
;         __builtin_amdgcn_global_load_lds((const unsigned*)((const char*)(gbase) + (voff)[_i]), (LAS unsigned*)(lds + (bufoff) + ldsw + _i * 8192), 16, 0, 0); } while (0)
; #define PG8_WAIT_V(n) asm volatile("s_waitcnt vmcnt(" #n ")" ::: "memory")
; #define PG8_BAR __builtin_amdgcn_s_barrier()
; template <class Epi, class Sched>
; __device__ __forceinline__ void gemm_phase(LAS unsigned char* lds, const Gemm g, const Sched& S, const Epi& E) {
;     ...
;     const unsigned ldsw = (unsigned)wid * 1024u;
;     const int aoff = lds_byte(wr * 64 + fr, fq * 8), boff = lds_byte(wc * 32 + fr, fq * 8);
;     ...
;     PG8_STAGE(PG8_SB(0, 0), cB, voffB); PG8_STAGE(PG8_SA(0, 0), cA, voffA); PG8_STAGE(PG8_SB(0, 1), cB + hstep, voffB); PG8_STAGE(PG8_SA(0, 1), cA + hstep, voffA);
;     if (wr == 1) PG8_BAR;
;     PG8_WAIT_V(4); PG8_BAR;
;     PG8_STAGE(PG8_SB(1, 0), cB + kstep, voffB); PG8_STAGE(PG8_SA(1, 0), cA + kstep, voffA); PG8_STAGE(PG8_SB(1, 1), cB + hstep + kstep, voffB);
;     PG8_WAIT_V(6); PG8_BAR;
.LBB0_642:
	v_lshrrev_b32_e32 v18, 1, v6
	v_and_b32_e32 v18, 24, v18
	s_lshl_b32 s1, s1, 5
	v_mov_b32_e32 v145, v8
	v_and_b32_e32 v7, 15, v6
	v_lshlrev_b32_e32 v19, 1, v18
	v_lshlrev_b32_e32 v6, 2, v6
	s_and_b32 s18, s1, 0x60
	v_lshl_add_u64 v[10:11], s[70:71], 0, v[144:145]
	v_mov_b32_e32 v141, v8
	v_lshl_or_b32 v9, s14, 6, v7
	v_lshl_or_b32 v7, v7, 6, v19
	s_lshl_b32 s14, s14, 13
	v_and_b32_e32 v6, 32, v6
	s_lshl_b32 s1, s18, 7
	v_lshl_add_u64 v[12:13], s[70:71], 0, v[140:141]
	v_mov_b32_e32 v147, v8
	v_bitop3_b32 v19, v7, s14, v6 bitop3:0xde
	v_bitop3_b32 v152, v7, s1, v6 bitop3:0xde
	s_add_i32 m0, s11, 0x18000
	v_lshl_add_u64 v[6:7], v[10:11], 0, s[94:95]
	v_lshl_add_u64 v[14:15], s[78:79], 0, v[146:147]
	v_mov_b32_e32 v143, v8
	s_waitcnt vmcnt(4)
	s_barrier
	global_load_lds_dwordx4 v[6:7], off
	v_lshl_add_u64 v[6:7], v[12:13], 0, s[94:95]
	s_add_i32 m0, s11, 0x1a000
	s_add_i32 s14, s11, 0x8000
	s_add_i32 s15, s11, 0xa000
	v_lshl_add_u64 v[16:17], s[78:79], 0, v[142:143]
	global_load_lds_dwordx4 v[6:7], off
	v_lshl_add_u64 v[6:7], v[14:15], 0, s[94:95]
	s_mov_b32 m0, s14
	s_add_u32 s16, s70, 0x40080
	global_load_lds_dwordx4 v[6:7], off
	v_lshl_add_u64 v[6:7], v[16:17], 0, s[94:95]
	s_mov_b32 m0, s15
	s_addc_u32 s17, s71, 0
	global_load_lds_dwordx4 v[6:7], off
	s_add_i32 m0, s11, 0x1c000
	v_lshl_add_u64 v[6:7], s[16:17], 0, v[144:145]
	global_load_lds_dwordx4 v[6:7], off
	v_lshl_add_u64 v[6:7], s[16:17], 0, v[140:141]
	s_add_i32 m0, s11, 0x1e000
	s_mov_b32 s1, s3
	global_load_lds_dwordx4 v[6:7], off
	v_lshlrev_b32_e32 v6, 14, v4
	v_and_b32_e32 v6, 0xffff8000, v6
	v_lshl_add_u32 v3, v3, 11, v6
	v_and_b32_e32 v4, 1, v4
	v_lshl_or_b32 v3, v4, 6, v3
	v_lshl_add_u32 v148, v5, 1, v3
	v_lshlrev_b32_e32 v3, 14, v0
	v_and_b32_e32 v3, 0xffff8000, v3
	s_waitcnt vmcnt(6)
	v_lshl_add_u32 v1, v1, 11, v3
	v_and_b32_e32 v0, 1, v0
	v_lshl_or_b32 v0, v0, 6, v1
	v_or_b32_e32 v153, s18, v18
	v_mov_b32_e32 v149, v8
	v_lshl_add_u32 v150, v2, 1, v0
	v_mov_b32_e32 v151, v8
	s_mov_b32 s43, 0
	v_add_u32_e32 v154, 16, v19
	s_barrier
	s_cmp_lg_u32 s46, 0x100
	s_cbranch_scc1 .Lds643_x
	s_bfe_u32 s98, s92, 0x20003
	s_lshl_b32 s98, s98, 2
	s_cmp_eq_u32 s98, 0
	s_cbranch_scc1 .Lds643_x
	s_min_u32 s98, s98, 16
